# np13 + nt (streaming) cache policy on the read-once f32 input loads of the prep phase
# speedup vs baseline: 1.0116x; 1.0116x over previous
.LBB0_52:
	s_cmpk_gt_i32 s90, 0x27f
	s_mov_b64 s[14:15], -1
	s_cbranch_scc0 .LBB0_62
	s_cmpk_gt_u32 s90, 0x2bf
	s_cbranch_scc0 .LBB0_59
	s_cmpk_gt_u32 s90, 0x2ff
	s_cbranch_scc0 .LBB0_56
	s_bfe_u32 s16, s90, 0x60002
	s_lshl_b32 s14, s90, 8
	s_lshl_b32 s15, s16, 10
	s_sub_i32 s14, s14, s15
	s_add_i32 s14, s14, 0xfffd0000
	s_ashr_i32 s15, s14, 31
	v_lshlrev_b32_e32 v4, 12, v57
	v_lshl_add_u64 v[2:3], s[14:15], 2, v[66:67]
	v_lshl_or_b32 v54, s16, 18, v4
	v_lshl_add_u64 v[30:31], v[2:3], 0, v[54:55]
	v_add_co_u32_e32 v6, vcc, 0x8000, v30
	v_add_u32_e32 v36, v112, v117
	s_nop 0
	v_addc_co_u32_e32 v7, vcc, 0, v31, vcc
	v_add_co_u32_e32 v10, vcc, 0x10000, v30
	global_load_dwordx4 v[2:5], v[30:31], off nt
	s_nop 0
	global_load_dwordx4 v[6:9], v[6:7], off nt
	v_addc_co_u32_e32 v11, vcc, 0, v31, vcc
	v_add_co_u32_e32 v14, vcc, 0x18000, v30
	v_add_u32_e32 v37, 0x2020, v36
	s_nop 0
	v_addc_co_u32_e32 v15, vcc, 0, v31, vcc
	v_add_co_u32_e32 v18, vcc, 0x20000, v30
	global_load_dwordx4 v[10:13], v[10:11], off nt
	s_nop 0
	global_load_dwordx4 v[14:17], v[14:15], off nt
	v_addc_co_u32_e32 v19, vcc, 0, v31, vcc
	v_add_co_u32_e32 v22, vcc, 0x28000, v30
	v_add_u32_e32 v38, 0x2028, v36
	s_nop 0
	v_addc_co_u32_e32 v23, vcc, 0, v31, vcc
	global_load_dwordx4 v[18:21], v[18:19], off nt
	s_nop 0
	global_load_dwordx4 v[22:25], v[22:23], off nt
	v_add_co_u32_e32 v26, vcc, 0x30000, v30
	v_add_u32_e32 v39, 0x4040, v36
	s_nop 0
	v_addc_co_u32_e32 v27, vcc, 0, v31, vcc
	global_load_dwordx4 v[26:29], v[26:27], off nt
	v_add_co_u32_e32 v30, vcc, 0x38000, v30
	v_add_u32_e32 v40, 0x4048, v36
	s_nop 0
	v_addc_co_u32_e32 v31, vcc, 0, v31, vcc
	global_load_dwordx4 v[30:33], v[30:31], off nt
	v_add_u32_e32 v41, 0x6060, v36
	v_add_u32_e32 v42, 0x6068, v36
	v_add_u32_e32 v43, 0x8080, v36
	v_add_u32_e32 v44, 0x8088, v36
	v_add_u32_e32 v45, 0xa0a0, v36
	v_add_u32_e32 v46, 0xa0a8, v36
	v_add_u32_e32 v47, 0xc0c0, v36
	v_add_u32_e32 v48, 0xc0c8, v36
	v_add_u32_e32 v49, 0xe0e0, v36
	v_add_u32_e32 v50, 0xe0e8, v36
	v_add_u32_e32 v34, s14, v113
	v_ashrrev_i32_e32 v35, 31, v34
	v_lshlrev_b64 v[34:35], 11, v[34:35]
	s_lshl_b32 s30, s16, 7
	v_lshl_add_u64 v[34:35], s[96:97], 0, v[34:35]
	v_lshlrev_b32_e32 v54, 1, v56
	v_lshl_add_u64 v[34:35], v[34:35], 0, s[30:31]
	s_mov_b64 s[14:15], 0
	s_waitcnt vmcnt(7)
	ds_write2_b32 v36, v2, v3 offset1:1
	ds_write2_b32 v36, v4, v5 offset0:2 offset1:3
	s_waitcnt vmcnt(6)
	ds_write2_b32 v37, v6, v7 offset1:1
	ds_write2_b32 v38, v8, v9 offset1:1
	s_waitcnt vmcnt(5)
	ds_write2_b32 v39, v10, v11 offset1:1
	ds_write2_b32 v40, v12, v13 offset1:1
	s_waitcnt vmcnt(4)
	ds_write2_b32 v41, v14, v15 offset1:1
	ds_write2_b32 v42, v16, v17 offset1:1
	s_waitcnt vmcnt(3)
	ds_write2_b32 v43, v18, v19 offset1:1
	ds_write2_b32 v44, v20, v21 offset1:1
	s_waitcnt vmcnt(2)
	ds_write2_b32 v45, v22, v23 offset1:1
	ds_write2_b32 v46, v24, v25 offset1:1
	s_waitcnt vmcnt(1)
	ds_write2_b32 v47, v26, v27 offset1:1
	ds_write2_b32 v48, v28, v29 offset1:1
	s_waitcnt vmcnt(0)
	ds_write2_b32 v49, v30, v31 offset1:1
	ds_write2_b32 v50, v32, v33 offset1:1
	s_waitcnt lgkmcnt(0)
	s_barrier
	ds_read_b32 v2, v114
	ds_read_b32 v3, v114 offset:1028
	ds_read_b32 v4, v114 offset:2056
	ds_read_b32 v5, v114 offset:3084
	ds_read_b32 v8, v114 offset:4112
	ds_read_b32 v9, v114 offset:5140
	ds_read_b32 v10, v114 offset:6168
	ds_read_b32 v11, v114 offset:7196
	s_waitcnt lgkmcnt(6)
	v_cvt_pk_bf16_f32 v2, v2, v3
	s_waitcnt lgkmcnt(4)
	v_cvt_pk_bf16_f32 v3, v4, v5
	s_waitcnt lgkmcnt(2)
	v_cvt_pk_bf16_f32 v4, v8, v9
	v_lshl_add_u64 v[6:7], v[34:35], 0, v[54:55]
	s_waitcnt lgkmcnt(0)
	v_cvt_pk_bf16_f32 v5, v10, v11
	ds_read_b32 v8, v114 offset:8224
	ds_read_b32 v9, v114 offset:9252
	ds_read_b32 v10, v114 offset:10280
	ds_read_b32 v11, v114 offset:11308
	ds_read_b32 v12, v114 offset:12336
	ds_read_b32 v13, v114 offset:13364
	ds_read_b32 v14, v114 offset:14392
	ds_read_b32 v15, v114 offset:15420
	global_store_dwordx4 v[6:7], v[2:5], off
	s_waitcnt lgkmcnt(6)
	s_nop 0
	v_cvt_pk_bf16_f32 v2, v8, v9
	s_waitcnt lgkmcnt(4)
	v_cvt_pk_bf16_f32 v3, v10, v11
	s_waitcnt lgkmcnt(2)
	v_cvt_pk_bf16_f32 v4, v12, v13
	s_waitcnt lgkmcnt(0)
	v_cvt_pk_bf16_f32 v5, v14, v15
	ds_read_b32 v8, v114 offset:16448
	ds_read_b32 v9, v114 offset:17476
	ds_read_b32 v10, v114 offset:18504
	ds_read_b32 v11, v114 offset:19532
	ds_read_b32 v12, v114 offset:20560
	ds_read_b32 v13, v114 offset:21588
	ds_read_b32 v14, v114 offset:22616
	ds_read_b32 v15, v114 offset:23644
	global_store_dwordx4 v[6:7], v[2:5], off offset:16
	s_waitcnt lgkmcnt(6)
	s_nop 0
	v_cvt_pk_bf16_f32 v2, v8, v9
	s_waitcnt lgkmcnt(4)
	v_cvt_pk_bf16_f32 v3, v10, v11
	s_waitcnt lgkmcnt(2)
	v_cvt_pk_bf16_f32 v4, v12, v13
	s_waitcnt lgkmcnt(0)
	v_cvt_pk_bf16_f32 v5, v14, v15
	ds_read_b32 v8, v114 offset:24672
	ds_read_b32 v9, v114 offset:25700
	ds_read_b32 v10, v114 offset:26728
	ds_read_b32 v11, v114 offset:27756
	ds_read_b32 v12, v114 offset:28784
	ds_read_b32 v13, v114 offset:29812
	ds_read_b32 v14, v114 offset:30840
	ds_read_b32 v15, v114 offset:31868
	global_store_dwordx4 v[6:7], v[2:5], off offset:32
	s_waitcnt lgkmcnt(6)
	s_nop 0
	v_cvt_pk_bf16_f32 v2, v8, v9
	s_waitcnt lgkmcnt(4)
	v_cvt_pk_bf16_f32 v3, v10, v11
	s_waitcnt lgkmcnt(2)
	v_cvt_pk_bf16_f32 v4, v12, v13
	s_waitcnt lgkmcnt(0)
	v_cvt_pk_bf16_f32 v5, v14, v15
	global_store_dwordx4 v[6:7], v[2:5], off offset:48
	s_barrier
.LBB0_56:
	s_andn2_b64 vcc, exec, s[14:15]
	s_cbranch_vccnz .LBB0_58
	s_add_i32 s14, s90, 0xfffffd40
	s_lshr_b32 s16, s14, 2
	s_lshl_b32 s15, s16, 10
	s_lshl_b32 s14, s14, 8
	s_sub_i32 s14, s14, s15
	v_lshl_or_b32 v4, s16, 6, v57
	s_ashr_i32 s15, s14, 31
	v_lshl_add_u64 v[2:3], s[14:15], 2, v[68:69]
	v_lshlrev_b32_e32 v54, 10, v4
	v_lshl_add_u64 v[30:31], v[54:55], 2, v[2:3]
	v_add_co_u32_e32 v6, vcc, 0x8000, v30
	v_add_u32_e32 v36, v112, v117
	s_nop 0
	v_addc_co_u32_e32 v7, vcc, 0, v31, vcc
	v_add_co_u32_e32 v10, vcc, 0x10000, v30
	global_load_dwordx4 v[2:5], v[30:31], off nt
	s_nop 0
	global_load_dwordx4 v[6:9], v[6:7], off nt
	v_addc_co_u32_e32 v11, vcc, 0, v31, vcc
	v_add_co_u32_e32 v14, vcc, 0x18000, v30
	v_add_u32_e32 v37, 0x2020, v36
	s_nop 0
	v_addc_co_u32_e32 v15, vcc, 0, v31, vcc
	v_add_co_u32_e32 v18, vcc, 0x20000, v30
	global_load_dwordx4 v[10:13], v[10:11], off nt
	s_nop 0
	global_load_dwordx4 v[14:17], v[14:15], off nt
	v_addc_co_u32_e32 v19, vcc, 0, v31, vcc
	v_add_co_u32_e32 v22, vcc, 0x28000, v30
	v_add_u32_e32 v38, 0x2028, v36
	s_nop 0
	v_addc_co_u32_e32 v23, vcc, 0, v31, vcc
	global_load_dwordx4 v[18:21], v[18:19], off nt
	s_nop 0
	global_load_dwordx4 v[22:25], v[22:23], off nt
	v_add_co_u32_e32 v26, vcc, 0x30000, v30
	v_add_u32_e32 v39, 0x4040, v36
	s_nop 0
	v_addc_co_u32_e32 v27, vcc, 0, v31, vcc
	global_load_dwordx4 v[26:29], v[26:27], off nt
	v_add_co_u32_e32 v30, vcc, 0x38000, v30
	v_add_u32_e32 v40, 0x4048, v36
	s_nop 0
	v_addc_co_u32_e32 v31, vcc, 0, v31, vcc
	global_load_dwordx4 v[30:33], v[30:31], off nt
	v_add_u32_e32 v41, 0x6060, v36
	v_add_u32_e32 v42, 0x6068, v36
	v_add_u32_e32 v43, 0x8080, v36
	v_add_u32_e32 v44, 0x8088, v36
	v_add_u32_e32 v45, 0xa0a0, v36
	v_add_u32_e32 v46, 0xa0a8, v36
	v_add_u32_e32 v47, 0xc0c0, v36
	v_add_u32_e32 v48, 0xc0c8, v36
	v_add_u32_e32 v49, 0xe0e0, v36
	v_add_u32_e32 v50, 0xe0e8, v36
	v_add_u32_e32 v34, s14, v113
	v_ashrrev_i32_e32 v35, 31, v34
	v_lshlrev_b64 v[34:35], 11, v[34:35]
	s_lshl_b32 s30, s16, 7
	v_lshl_add_u64 v[34:35], s[28:29], 0, v[34:35]
	v_lshlrev_b32_e32 v54, 1, v56
	v_lshl_add_u64 v[34:35], v[34:35], 0, s[30:31]
	s_waitcnt vmcnt(7)
	ds_write2_b32 v36, v2, v3 offset1:1
	ds_write2_b32 v36, v4, v5 offset0:2 offset1:3
	s_waitcnt vmcnt(6)
	ds_write2_b32 v37, v6, v7 offset1:1
	ds_write2_b32 v38, v8, v9 offset1:1
	s_waitcnt vmcnt(5)
	ds_write2_b32 v39, v10, v11 offset1:1
	ds_write2_b32 v40, v12, v13 offset1:1
	s_waitcnt vmcnt(4)
	ds_write2_b32 v41, v14, v15 offset1:1
	ds_write2_b32 v42, v16, v17 offset1:1
	s_waitcnt vmcnt(3)
	ds_write2_b32 v43, v18, v19 offset1:1
	ds_write2_b32 v44, v20, v21 offset1:1
	s_waitcnt vmcnt(2)
	ds_write2_b32 v45, v22, v23 offset1:1
	ds_write2_b32 v46, v24, v25 offset1:1
	s_waitcnt vmcnt(1)
	ds_write2_b32 v47, v26, v27 offset1:1
	ds_write2_b32 v48, v28, v29 offset1:1
	s_waitcnt vmcnt(0)
	ds_write2_b32 v49, v30, v31 offset1:1
	ds_write2_b32 v50, v32, v33 offset1:1
	s_waitcnt lgkmcnt(0)
	s_barrier
	ds_read_b32 v2, v114
	ds_read_b32 v3, v114 offset:1028
	ds_read_b32 v4, v114 offset:2056
	ds_read_b32 v5, v114 offset:3084
	ds_read_b32 v8, v114 offset:4112
	ds_read_b32 v9, v114 offset:5140
	ds_read_b32 v10, v114 offset:6168
	ds_read_b32 v11, v114 offset:7196
	s_waitcnt lgkmcnt(6)
	v_cvt_pk_bf16_f32 v2, v2, v3
	s_waitcnt lgkmcnt(4)
	v_cvt_pk_bf16_f32 v3, v4, v5
	s_waitcnt lgkmcnt(2)
	v_cvt_pk_bf16_f32 v4, v8, v9
	v_lshl_add_u64 v[6:7], v[34:35], 0, v[54:55]
	s_waitcnt lgkmcnt(0)
	v_cvt_pk_bf16_f32 v5, v10, v11
	ds_read_b32 v8, v114 offset:8224
	ds_read_b32 v9, v114 offset:9252
	ds_read_b32 v10, v114 offset:10280
	ds_read_b32 v11, v114 offset:11308
	ds_read_b32 v12, v114 offset:12336
	ds_read_b32 v13, v114 offset:13364
	ds_read_b32 v14, v114 offset:14392
	ds_read_b32 v15, v114 offset:15420
	global_store_dwordx4 v[6:7], v[2:5], off
	s_waitcnt lgkmcnt(6)
	s_nop 0
	v_cvt_pk_bf16_f32 v2, v8, v9
	s_waitcnt lgkmcnt(4)
	v_cvt_pk_bf16_f32 v3, v10, v11
	s_waitcnt lgkmcnt(2)
	v_cvt_pk_bf16_f32 v4, v12, v13
	s_waitcnt lgkmcnt(0)
	v_cvt_pk_bf16_f32 v5, v14, v15
	ds_read_b32 v8, v114 offset:16448
	ds_read_b32 v9, v114 offset:17476
	ds_read_b32 v10, v114 offset:18504
	ds_read_b32 v11, v114 offset:19532
	ds_read_b32 v12, v114 offset:20560
	ds_read_b32 v13, v114 offset:21588
	ds_read_b32 v14, v114 offset:22616
	ds_read_b32 v15, v114 offset:23644
	global_store_dwordx4 v[6:7], v[2:5], off offset:16
	s_waitcnt lgkmcnt(6)
	s_nop 0
	v_cvt_pk_bf16_f32 v2, v8, v9
	s_waitcnt lgkmcnt(4)
	v_cvt_pk_bf16_f32 v3, v10, v11
	s_waitcnt lgkmcnt(2)
	v_cvt_pk_bf16_f32 v4, v12, v13
	s_waitcnt lgkmcnt(0)
	v_cvt_pk_bf16_f32 v5, v14, v15
	ds_read_b32 v8, v114 offset:24672
	ds_read_b32 v9, v114 offset:25700
	ds_read_b32 v10, v114 offset:26728
	ds_read_b32 v11, v114 offset:27756
	ds_read_b32 v12, v114 offset:28784
	ds_read_b32 v13, v114 offset:29812
	ds_read_b32 v14, v114 offset:30840
	ds_read_b32 v15, v114 offset:31868
	global_store_dwordx4 v[6:7], v[2:5], off offset:32
	s_waitcnt lgkmcnt(6)
	s_nop 0
	v_cvt_pk_bf16_f32 v2, v8, v9
	s_waitcnt lgkmcnt(4)
	v_cvt_pk_bf16_f32 v3, v10, v11
	s_waitcnt lgkmcnt(2)
	v_cvt_pk_bf16_f32 v4, v12, v13
	s_waitcnt lgkmcnt(0)
	v_cvt_pk_bf16_f32 v5, v14, v15
	global_store_dwordx4 v[6:7], v[2:5], off offset:48
	s_barrier

.LBB0_59:
	s_andn2_b64 vcc, exec, s[14:15]
	s_cbranch_vccnz .LBB0_61
	s_add_i32 s14, s90, 0xfffffd80
	s_lshr_b32 s16, s14, 2
	s_lshl_b32 s15, s16, 10
	s_lshl_b32 s14, s14, 8
	s_sub_i32 s14, s14, s15
	v_lshl_or_b32 v4, s16, 6, v57
	s_ashr_i32 s15, s14, 31
	v_lshl_add_u64 v[2:3], s[14:15], 2, v[70:71]
	v_lshlrev_b32_e32 v54, 10, v4
	v_lshl_add_u64 v[30:31], v[54:55], 2, v[2:3]
	v_add_co_u32_e32 v6, vcc, 0x8000, v30
	v_add_u32_e32 v36, v112, v117
	s_nop 0
	v_addc_co_u32_e32 v7, vcc, 0, v31, vcc
	v_add_co_u32_e32 v10, vcc, 0x10000, v30
	global_load_dwordx4 v[2:5], v[30:31], off nt
	s_nop 0
	global_load_dwordx4 v[6:9], v[6:7], off nt
	v_addc_co_u32_e32 v11, vcc, 0, v31, vcc
	v_add_co_u32_e32 v14, vcc, 0x18000, v30
	v_add_u32_e32 v37, 0x2020, v36
	s_nop 0
	v_addc_co_u32_e32 v15, vcc, 0, v31, vcc
	v_add_co_u32_e32 v18, vcc, 0x20000, v30
	global_load_dwordx4 v[10:13], v[10:11], off nt
	s_nop 0
	global_load_dwordx4 v[14:17], v[14:15], off nt
	v_addc_co_u32_e32 v19, vcc, 0, v31, vcc
	v_add_co_u32_e32 v22, vcc, 0x28000, v30
	v_add_u32_e32 v38, 0x2028, v36
	s_nop 0
	v_addc_co_u32_e32 v23, vcc, 0, v31, vcc
	global_load_dwordx4 v[18:21], v[18:19], off nt
	s_nop 0
	global_load_dwordx4 v[22:25], v[22:23], off nt
	v_add_co_u32_e32 v26, vcc, 0x30000, v30
	v_add_u32_e32 v39, 0x4040, v36
	s_nop 0
	v_addc_co_u32_e32 v27, vcc, 0, v31, vcc
	global_load_dwordx4 v[26:29], v[26:27], off nt
	v_add_co_u32_e32 v30, vcc, 0x38000, v30
	v_add_u32_e32 v40, 0x4048, v36
	s_nop 0
	v_addc_co_u32_e32 v31, vcc, 0, v31, vcc
	global_load_dwordx4 v[30:33], v[30:31], off nt
	v_add_u32_e32 v41, 0x6060, v36
	v_add_u32_e32 v42, 0x6068, v36
	v_add_u32_e32 v43, 0x8080, v36
	v_add_u32_e32 v44, 0x8088, v36
	v_add_u32_e32 v45, 0xa0a0, v36
	v_add_u32_e32 v46, 0xa0a8, v36
	v_add_u32_e32 v47, 0xc0c0, v36
	v_add_u32_e32 v48, 0xc0c8, v36
	v_add_u32_e32 v49, 0xe0e0, v36
	v_add_u32_e32 v50, 0xe0e8, v36
	v_add_u32_e32 v34, s14, v113
	v_ashrrev_i32_e32 v35, 31, v34
	v_lshlrev_b64 v[34:35], 11, v[34:35]
	s_lshl_b32 s30, s16, 7
	v_lshl_add_u64 v[34:35], s[54:55], 0, v[34:35]
	v_lshlrev_b32_e32 v54, 1, v56
	v_lshl_add_u64 v[34:35], v[34:35], 0, s[30:31]
	s_waitcnt vmcnt(7)
	ds_write2_b32 v36, v2, v3 offset1:1
	ds_write2_b32 v36, v4, v5 offset0:2 offset1:3
	s_waitcnt vmcnt(6)
	ds_write2_b32 v37, v6, v7 offset1:1
	ds_write2_b32 v38, v8, v9 offset1:1
	s_waitcnt vmcnt(5)
	ds_write2_b32 v39, v10, v11 offset1:1
	ds_write2_b32 v40, v12, v13 offset1:1
	s_waitcnt vmcnt(4)
	ds_write2_b32 v41, v14, v15 offset1:1
	ds_write2_b32 v42, v16, v17 offset1:1
	s_waitcnt vmcnt(3)
	ds_write2_b32 v43, v18, v19 offset1:1
	ds_write2_b32 v44, v20, v21 offset1:1
	s_waitcnt vmcnt(2)
	ds_write2_b32 v45, v22, v23 offset1:1
	ds_write2_b32 v46, v24, v25 offset1:1
	s_waitcnt vmcnt(1)
	ds_write2_b32 v47, v26, v27 offset1:1
	ds_write2_b32 v48, v28, v29 offset1:1
	s_waitcnt vmcnt(0)
	ds_write2_b32 v49, v30, v31 offset1:1
	ds_write2_b32 v50, v32, v33 offset1:1
	s_waitcnt lgkmcnt(0)
	s_barrier
	ds_read_b32 v2, v114
	ds_read_b32 v3, v114 offset:1028
	ds_read_b32 v4, v114 offset:2056
	ds_read_b32 v5, v114 offset:3084
	ds_read_b32 v8, v114 offset:4112
	ds_read_b32 v9, v114 offset:5140
	ds_read_b32 v10, v114 offset:6168
	ds_read_b32 v11, v114 offset:7196
	s_waitcnt lgkmcnt(6)
	v_cvt_pk_bf16_f32 v2, v2, v3
	s_waitcnt lgkmcnt(4)
	v_cvt_pk_bf16_f32 v3, v4, v5
	s_waitcnt lgkmcnt(2)
	v_cvt_pk_bf16_f32 v4, v8, v9
	v_lshl_add_u64 v[6:7], v[34:35], 0, v[54:55]
	s_waitcnt lgkmcnt(0)
	v_cvt_pk_bf16_f32 v5, v10, v11
	ds_read_b32 v8, v114 offset:8224
	ds_read_b32 v9, v114 offset:9252
	ds_read_b32 v10, v114 offset:10280
	ds_read_b32 v11, v114 offset:11308
	ds_read_b32 v12, v114 offset:12336
	ds_read_b32 v13, v114 offset:13364
	ds_read_b32 v14, v114 offset:14392
	ds_read_b32 v15, v114 offset:15420
	global_store_dwordx4 v[6:7], v[2:5], off
	s_waitcnt lgkmcnt(6)
	s_nop 0
	v_cvt_pk_bf16_f32 v2, v8, v9
	s_waitcnt lgkmcnt(4)
	v_cvt_pk_bf16_f32 v3, v10, v11
	s_waitcnt lgkmcnt(2)
	v_cvt_pk_bf16_f32 v4, v12, v13
	s_waitcnt lgkmcnt(0)
	v_cvt_pk_bf16_f32 v5, v14, v15
	ds_read_b32 v8, v114 offset:16448
	ds_read_b32 v9, v114 offset:17476
	ds_read_b32 v10, v114 offset:18504
	ds_read_b32 v11, v114 offset:19532
	ds_read_b32 v12, v114 offset:20560
	ds_read_b32 v13, v114 offset:21588
	ds_read_b32 v14, v114 offset:22616
	ds_read_b32 v15, v114 offset:23644
	global_store_dwordx4 v[6:7], v[2:5], off offset:16
	s_waitcnt lgkmcnt(6)
	s_nop 0
	v_cvt_pk_bf16_f32 v2, v8, v9
	s_waitcnt lgkmcnt(4)
	v_cvt_pk_bf16_f32 v3, v10, v11
	s_waitcnt lgkmcnt(2)
	v_cvt_pk_bf16_f32 v4, v12, v13
	s_waitcnt lgkmcnt(0)
	v_cvt_pk_bf16_f32 v5, v14, v15
	ds_read_b32 v8, v114 offset:24672
	ds_read_b32 v9, v114 offset:25700
	ds_read_b32 v10, v114 offset:26728
	ds_read_b32 v11, v114 offset:27756
	ds_read_b32 v12, v114 offset:28784
	ds_read_b32 v13, v114 offset:29812
	ds_read_b32 v14, v114 offset:30840
	ds_read_b32 v15, v114 offset:31868
	global_store_dwordx4 v[6:7], v[2:5], off offset:32
	s_waitcnt lgkmcnt(6)
	s_nop 0
	v_cvt_pk_bf16_f32 v2, v8, v9
	s_waitcnt lgkmcnt(4)
	v_cvt_pk_bf16_f32 v3, v10, v11
	s_waitcnt lgkmcnt(2)
	v_cvt_pk_bf16_f32 v4, v12, v13
	s_waitcnt lgkmcnt(0)
	v_cvt_pk_bf16_f32 v5, v14, v15
	global_store_dwordx4 v[6:7], v[2:5], off offset:48
	s_barrier

.LBB0_62:
	s_andn2_b64 vcc, exec, s[14:15]
	s_cbranch_vccnz .LBB0_64
	s_mul_hi_i32 s14, s90, 0x66666667
	s_lshr_b32 s15, s14, 31
	s_ashr_i32 s14, s14, 4
	s_add_i32 s14, s14, s15
	s_mul_i32 s15, s14, 0xffffffd8
	s_add_i32 s15, s15, s90
	s_lshl_b32 s14, s14, 6
	s_lshl_b32 s16, s15, 8
	v_or_b32_e32 v32, s14, v57
	s_ashr_i32 s17, s16, 31
	v_lshl_add_u64 v[30:31], s[16:17], 2, v[72:73]
	v_add_u32_e32 v4, 8, v32
	v_or_b32_e32 v10, 16, v32
	v_add_u32_e32 v12, 24, v32
	v_or_b32_e32 v18, 32, v32
	v_add_u32_e32 v20, 40, v32
	v_mad_i64_i32 v[2:3], s[36:37], v32, s85, v[30:31]
	v_mad_i64_i32 v[6:7], s[36:37], v4, s85, v[30:31]
	v_mad_i64_i32 v[10:11], s[36:37], v10, s85, v[30:31]
	v_mad_i64_i32 v[14:15], s[36:37], v12, s85, v[30:31]
	v_mad_i64_i32 v[18:19], s[36:37], v18, s85, v[30:31]
	v_mad_i64_i32 v[22:23], s[36:37], v20, s85, v[30:31]
	global_load_dwordx4 v[2:5], v[2:3], off nt
	s_nop 0
	global_load_dwordx4 v[6:9], v[6:7], off nt
	s_nop 0
	global_load_dwordx4 v[10:13], v[10:11], off nt
	s_nop 0
	global_load_dwordx4 v[14:17], v[14:15], off nt
	s_nop 0
	global_load_dwordx4 v[18:21], v[18:19], off nt
	s_nop 0
	global_load_dwordx4 v[22:25], v[22:23], off nt
	v_or_b32_e32 v26, 48, v32
	v_mad_i64_i32 v[26:27], s[36:37], v26, s85, v[30:31]
	global_load_dwordx4 v[26:29], v[26:27], off nt
	v_add_u32_e32 v32, 56, v32
	v_mad_i64_i32 v[30:31], s[36:37], v32, s85, v[30:31]
	global_load_dwordx4 v[30:33], v[30:31], off nt
	v_add_u32_e32 v36, v112, v117
	v_add_u32_e32 v37, 0x2020, v36
	v_add_u32_e32 v38, 0x2028, v36
	v_add_u32_e32 v39, 0x4040, v36
	v_add_u32_e32 v40, 0x4048, v36
	v_add_u32_e32 v41, 0x6060, v36
	v_add_u32_e32 v42, 0x6068, v36
	v_add_u32_e32 v43, 0x8080, v36
	v_add_u32_e32 v44, 0x8088, v36
	v_add_u32_e32 v45, 0xa0a0, v36
	v_add_u32_e32 v46, 0xa0a8, v36
	v_add_u32_e32 v47, 0xc0c0, v36
	v_add_u32_e32 v48, 0xc0c8, v36
	v_add_u32_e32 v49, 0xe0e0, v36
	v_add_u32_e32 v50, 0xe0e8, v36
	v_add_u32_e32 v34, s16, v113
	v_ashrrev_i32_e32 v35, 31, v34
	v_lshlrev_b64 v[34:35], 11, v[34:35]
	s_ashr_i32 s15, s14, 31
	v_lshl_add_u64 v[34:35], s[66:67], 0, v[34:35]
	v_lshlrev_b32_e32 v54, 1, v56
	v_lshl_add_u64 v[34:35], s[14:15], 1, v[34:35]
	s_waitcnt vmcnt(7)
	ds_write2_b32 v36, v2, v3 offset1:1
	ds_write2_b32 v36, v4, v5 offset0:2 offset1:3
	s_waitcnt vmcnt(6)
	ds_write2_b32 v37, v6, v7 offset1:1
	ds_write2_b32 v38, v8, v9 offset1:1
	s_waitcnt vmcnt(5)
	ds_write2_b32 v39, v10, v11 offset1:1
	ds_write2_b32 v40, v12, v13 offset1:1
	s_waitcnt vmcnt(4)
	ds_write2_b32 v41, v14, v15 offset1:1
	ds_write2_b32 v42, v16, v17 offset1:1
	s_waitcnt vmcnt(3)
	ds_write2_b32 v43, v18, v19 offset1:1
	ds_write2_b32 v44, v20, v21 offset1:1
	s_waitcnt vmcnt(2)
	ds_write2_b32 v45, v22, v23 offset1:1
	ds_write2_b32 v46, v24, v25 offset1:1
	s_waitcnt vmcnt(1)
	ds_write2_b32 v47, v26, v27 offset1:1
	ds_write2_b32 v48, v28, v29 offset1:1
	s_waitcnt vmcnt(0)
	ds_write2_b32 v49, v30, v31 offset1:1
	ds_write2_b32 v50, v32, v33 offset1:1
	s_waitcnt lgkmcnt(0)
	s_barrier
	ds_read_b32 v2, v114
	ds_read_b32 v3, v114 offset:1028
	ds_read_b32 v4, v114 offset:2056
	ds_read_b32 v5, v114 offset:3084
	ds_read_b32 v8, v114 offset:4112
	ds_read_b32 v9, v114 offset:5140
	ds_read_b32 v10, v114 offset:6168
	ds_read_b32 v11, v114 offset:7196
	s_waitcnt lgkmcnt(6)
	v_cvt_pk_bf16_f32 v2, v2, v3
	s_waitcnt lgkmcnt(4)
	v_cvt_pk_bf16_f32 v3, v4, v5
	s_waitcnt lgkmcnt(2)
	v_cvt_pk_bf16_f32 v4, v8, v9
	v_lshl_add_u64 v[6:7], v[34:35], 0, v[54:55]
	s_waitcnt lgkmcnt(0)
	v_cvt_pk_bf16_f32 v5, v10, v11
	ds_read_b32 v8, v114 offset:8224
	ds_read_b32 v9, v114 offset:9252
	ds_read_b32 v10, v114 offset:10280
	ds_read_b32 v11, v114 offset:11308
	ds_read_b32 v12, v114 offset:12336
	ds_read_b32 v13, v114 offset:13364
	ds_read_b32 v14, v114 offset:14392
	ds_read_b32 v15, v114 offset:15420
	global_store_dwordx4 v[6:7], v[2:5], off
	s_waitcnt lgkmcnt(6)
	s_nop 0
	v_cvt_pk_bf16_f32 v2, v8, v9
	s_waitcnt lgkmcnt(4)
	v_cvt_pk_bf16_f32 v3, v10, v11
	s_waitcnt lgkmcnt(2)
	v_cvt_pk_bf16_f32 v4, v12, v13
	s_waitcnt lgkmcnt(0)
	v_cvt_pk_bf16_f32 v5, v14, v15
	ds_read_b32 v8, v114 offset:16448
	ds_read_b32 v9, v114 offset:17476
	ds_read_b32 v10, v114 offset:18504
	ds_read_b32 v11, v114 offset:19532
	ds_read_b32 v12, v114 offset:20560
	ds_read_b32 v13, v114 offset:21588
	ds_read_b32 v14, v114 offset:22616
	ds_read_b32 v15, v114 offset:23644
	global_store_dwordx4 v[6:7], v[2:5], off offset:16
	s_waitcnt lgkmcnt(6)
	s_nop 0
	v_cvt_pk_bf16_f32 v2, v8, v9
	s_waitcnt lgkmcnt(4)
	v_cvt_pk_bf16_f32 v3, v10, v11
	s_waitcnt lgkmcnt(2)
	v_cvt_pk_bf16_f32 v4, v12, v13
	s_waitcnt lgkmcnt(0)
	v_cvt_pk_bf16_f32 v5, v14, v15
	ds_read_b32 v8, v114 offset:24672
	ds_read_b32 v9, v114 offset:25700
	ds_read_b32 v10, v114 offset:26728
	ds_read_b32 v11, v114 offset:27756
	ds_read_b32 v12, v114 offset:28784
	ds_read_b32 v13, v114 offset:29812
	ds_read_b32 v14, v114 offset:30840
	ds_read_b32 v15, v114 offset:31868
	global_store_dwordx4 v[6:7], v[2:5], off offset:32
	s_waitcnt lgkmcnt(6)
	s_nop 0
	v_cvt_pk_bf16_f32 v2, v8, v9
	s_waitcnt lgkmcnt(4)
	v_cvt_pk_bf16_f32 v3, v10, v11
	s_waitcnt lgkmcnt(2)
	v_cvt_pk_bf16_f32 v4, v12, v13
	s_waitcnt lgkmcnt(0)
	v_cvt_pk_bf16_f32 v5, v14, v15
	global_store_dwordx4 v[6:7], v[2:5], off offset:48
	s_barrier
